# attention: second pass of an item starts with Q and its first K/V tile already on chip (requested during the last tile of the first pass)
# speedup vs baseline: 1.0057x; 1.0006x over previous
; DEVI void attn_item(const P& p, int item, char* smem) {
;     const int tid = threadIdx.x, lane = tid & 63, w = tid >> 6, fr = lane & 15, fq = lane >> 4;
;     const int qt = item & 63, kvh = (item >> 6) & 3, b = item >> 8;
;     const int head = kvh * 4 + w, q0 = qt * 64;
;     const bf16_t* Q = (const bf16_t*)(p.ws + OFF_B) + ((size_t)(b * SEQ + q0)) * 1024 + head * 64;
;     const bf16_t* KB = (const bf16_t*)(p.ws + OFF_D);
;     const bf16_t* VT = (const bf16_t*)(p.ws + OFF_D + 17 * MiB);
;     char* sK = smem;
;     char* sV = smem + 8192;
;     const float sinkv = p.sink[head] * LOG2E;
;     const bf16_t* SGT = (const bf16_t*)(p.ws + OFF_C) + ((size_t)(b * SEQ + q0)) * 1024 + head * 64;
;     bf16_t* OG = (bf16_t*)(p.ws + OFF_A) + ((size_t)(b * SEQ + q0)) * 1024 + head * 64;
.LBB0_1427:
	s_or_b64 exec, exec, s[2:3]
	s_cmpk_gt_i32 s86, 0x7ff
	s_barrier
	s_cbranch_scc1 .LBB0_1444
	v_xor_b32_e32 v4, v216, v172
	v_lshlrev_b32_e32 v4, 4, v4
	v_and_b32_e32 v4, 0x70, v4
	v_bfe_u32 v3, v172, 4, 2
	v_add_u32_e32 v123, 0, v4
	v_and_b32_e32 v4, 7, v172
	v_mov_b32_e32 v1, 0
	s_movk_i32 s2, 0x70
	v_and_b32_e32 v0, 0x70, v182
	v_and_b32_e32 v6, 14, v172
	v_bitop3_b32 v7, v175, v4, 3 bitop3:0x6c
	v_bitop3_b32 v4, v3, v4, 4 bitop3:0x36
	v_lshl_add_u64 v[98:99], s[54:55], 0, v[0:1]
	v_lshl_add_u64 v[100:101], s[0:1], 0, v[0:1]
	v_bitop3_b32 v0, v182, s2, v172 bitop3:0x48
	v_lshlrev_b32_e32 v125, 2, v3
	v_lshlrev_b32_e32 v8, 4, v4
	v_bitop3_b32 v4, v175, v6, 3 bitop3:0x6c
	v_add_u32_e32 v124, 0, v0
	v_sub_u32_e32 v0, v174, v125
	v_lshlrev_b32_e32 v9, 3, v4
	v_bitop3_b32 v4, v3, v6, 4 bitop3:0x36
	v_lshlrev_b32_e32 v2, 3, v3
	v_cmp_eq_u32_e32 vcc, 0, v3
	v_add_u32_e32 v126, 0x7f, v0
	v_lshrrev_b32_e32 v0, 2, v172
	v_lshlrev_b32_e32 v10, 3, v4
	v_bitop3_b32 v4, v3, v6, 8 bitop3:0x36
	v_bitop3_b32 v3, v3, v6, 12 bitop3:0x36
	v_lshl_add_u32 v5, v174, 7, 0
	v_and_b32_e32 v0, 8, v0
	v_add_u32_e32 v128, 32, v216
	v_lshlrev_b32_e32 v7, 4, v7
	v_lshlrev_b32_e32 v11, 3, v4
	v_lshlrev_b32_e32 v3, 3, v3
	v_and_b32_e32 v4, 16, v172
	s_mov_b32 s29, 0
	v_cndmask_b32_e64 v121, 0, 1.0, vcc
	v_lshlrev_b32_e32 v127, 7, v216
	v_lshlrev_b32_e32 v129, 7, v128
	s_lshl_b32 s34, s86, 6
	s_lshl_b32 s35, s27, 6
	v_lshlrev_b32_e32 v102, 1, v2
	v_mov_b32_e32 v103, v1
	v_lshlrev_b32_e32 v104, 1, v0
	v_mov_b32_e32 v105, v1
	s_movk_i32 s36, 0x2200
	v_lshlrev_b32_e32 v106, 1, v4
	v_mov_b32_e32 v107, v1
	v_add_u32_e32 v130, v5, v7
	v_add_u32_e32 v131, v5, v8
	s_movk_i32 s37, 0xfeff
	s_movk_i32 s38, 0x101
	s_movk_i32 s39, 0xfefe
	v_add_u32_e32 v132, v5, v9
	v_add_u32_e32 v133, v5, v10
	v_add_u32_e32 v134, v5, v11
	v_add_u32_e32 v135, v5, v3
	v_and_b32_e32 v2, 7, v172
	v_and_b32_e32 v3, 4, v2
	v_and_b32_e32 v4, 1, v2
	v_lshl_or_b32 v3, v4, 1, v3
	v_bfe_u32 v4, v216, 1, 3
	v_xor_b32_e32 v3, v3, v4
	v_bfe_u32 v4, v2, 1, 1
	v_lshlrev_b32_e32 v4, 3, v4
	v_lshl_or_b32 v124, v3, 4, v4
	v_xor_b32_e32 v228, 16, v124
	v_bfe_u32 v2, v172, 4, 2
	v_bfe_u32 v3, v174, 1, 3
	v_xor_b32_e32 v2, v2, v3
	v_lshl_add_u32 v132, v2, 4, v5
	v_xor_b32_e32 v134, 64, v132
	v_add_u32_e32 v133, v123, v127
	v_add_u32_e32 v135, v124, v127
	v_add_u32_e32 v217, v123, v129
	v_add_u32_e32 v229, v124, v129
	v_add_u32_e32 v214, v228, v127
	v_add_u32_e32 v215, v228, v129
	v_mov_b32_e32 v136, 0xf149f2ca
	s_mov_b32 s42, s86
	s_mov_b32 s99, 0
	s_branch .LBB0_1430

; DEVI void attn_item(const P& p, int item, char* smem) {
;     ...
;     for (int mh = 0; mh < 2; ++mh) {
;         const int mo = mh * 32;
;         bf16x8 Qf[2][2];
; #pragma unroll
;         for (int m = 0; m < 2; ++m)
; #pragma unroll
;             for (int kk = 0; kk < 2; ++kk) Qf[m][kk] = *(const bf16x8*)(Q + (size_t)(mo + 16 * m + fr) * 1024 + kk * 32 + fq * 8);
;         f32x4 O[4][2];
; #pragma unroll
;         for (int nd = 0; nd < 4; ++nd)
; #pragma unroll
;             for (int m = 0; m < 2; ++m) O[nd][m] = (f32x4){0.f, 0.f, 0.f, 0.f};
;         float mrow[2], lrow[2];
; #pragma unroll
;         for (int m = 0; m < 2; ++m) { mrow[m] = sinkv; lrow[m] = (fq == 0) ? 1.0f : 0.0f; }
;     ...
;                 const size_t off = (size_t)(mo + 16 * m + fr) * 1024 + 16 * nd + 4 * fq;
;                 const uint2 g = *(const uint2*)(SGT + off);
.LBB0_1432:
	v_or_b32_e32 v0, s4, v174
	v_lshlrev_b32_e32 v122, 10, v0
	v_lshlrev_b32_e32 v0, 11, v0
	v_or_b32_e32 v120, 0x4000, v122
	s_cmp_eq_u32 s99, 2
	s_cbranch_scc1 .Lat_qmov
	v_lshl_add_u64 v[2:3], v[108:109], 0, v[0:1]
	v_lshlrev_b32_e32 v0, 1, v120
	global_load_dwordx4 v[22:25], v[2:3], off
	global_load_dwordx4 v[26:29], v[2:3], off offset:64
	v_lshl_add_u64 v[2:3], v[108:109], 0, v[0:1]
	global_load_dwordx4 v[30:33], v[2:3], off
	global_load_dwordx4 v[34:37], v[2:3], off offset:64
	s_mov_b32 s99, 0
	s_branch .Lat_qdone
.Lat_qmov:
	v_mov_b32_e32 v22, v232
	v_mov_b32_e32 v23, v233
	v_mov_b32_e32 v24, v234
	v_mov_b32_e32 v25, v235
	v_mov_b32_e32 v26, v236
	v_mov_b32_e32 v27, v237
	v_mov_b32_e32 v28, v238
	v_mov_b32_e32 v29, v239
	v_mov_b32_e32 v30, v240
	v_mov_b32_e32 v31, v241
	v_mov_b32_e32 v32, v242
	v_mov_b32_e32 v33, v243
	v_mov_b32_e32 v34, v244
	v_mov_b32_e32 v35, v245
	v_mov_b32_e32 v36, v246
	v_mov_b32_e32 v37, v247
.Lat_qdone:
	v_or_b32_e32 v50, v122, v125
	v_lshlrev_b32_e32 v50, 1, v50
	v_mov_b32_e32 v51, 0
	v_lshl_add_u64 v[52:53], v[110:111], 0, v[50:51]
	global_load_dwordx2 v[206:207], v[52:53], off
	global_load_dwordx2 v[208:209], v[52:53], off offset:32
	global_load_dwordx2 v[210:211], v[52:53], off offset:64
	global_load_dwordx2 v[212:213], v[52:53], off offset:96
	v_or_b32_e32 v50, v120, v125
	v_lshlrev_b32_e32 v50, 1, v50
	v_lshl_add_u64 v[52:53], v[110:111], 0, v[50:51]
	global_load_dwordx2 v[218:219], v[52:53], off
	global_load_dwordx2 v[220:221], v[52:53], off offset:32
	global_load_dwordx2 v[222:223], v[52:53], off offset:64
	global_load_dwordx2 v[224:225], v[52:53], off offset:96
	v_mov_b32_e32 v2, v1
	v_mov_b32_e32 v3, v1
	v_mov_b32_e32 v0, v1
	v_mov_b64_e32 v[40:41], v[2:3]
	v_mov_b64_e32 v[16:17], v[2:3]
	v_mov_b64_e32 v[44:45], v[2:3]
	v_mov_b64_e32 v[12:13], v[2:3]
	v_mov_b64_e32 v[48:49], v[2:3]
	v_mov_b64_e32 v[8:9], v[2:3]
	v_mov_b64_e32 v[20:21], v[2:3]
	v_add_u32_e32 v140, s4, v137
	v_mov_b64_e32 v[38:39], v[0:1]
	v_mov_b64_e32 v[14:15], v[0:1]
	v_mov_b64_e32 v[42:43], v[0:1]
	v_mov_b64_e32 v[10:11], v[0:1]
	v_mov_b64_e32 v[46:47], v[0:1]
	v_mov_b64_e32 v[6:7], v[0:1]
	v_mov_b64_e32 v[18:19], v[0:1]
	v_mov_b64_e32 v[4:5], v[2:3]
	s_xor_b64 s[0:1], s[2:3], -1
	v_add_u32_e32 v141, 16, v140
	v_add_u32_e32 v142, -2, v140
	v_add_u32_e32 v143, -3, v140
	v_add_u32_e32 v144, -16, v140
	v_subrev_u32_e32 v145, 17, v140
	v_subrev_u32_e32 v146, 18, v140
	v_subrev_u32_e32 v147, 19, v140
	v_subrev_u32_e32 v148, 32, v140
	v_subrev_u32_e32 v149, 33, v140
	v_subrev_u32_e32 v150, 34, v140
	v_subrev_u32_e32 v151, 35, v140
	v_subrev_u32_e32 v152, 48, v140
	v_subrev_u32_e32 v153, 49, v140
	v_subrev_u32_e32 v154, 50, v140
	v_subrev_u32_e32 v155, 51, v140
	v_add_u32_e32 v156, 14, v140
	v_add_u32_e32 v157, 13, v140
	s_mov_b32 s28, 0
	s_mov_b32 s47, s43
	v_mov_b32_e32 v158, v121
	v_mov_b32_e32 v139, v121
	v_mov_b32_e32 v160, v138
	v_mov_b32_e32 v159, v138
	v_mov_b64_e32 v[2:3], v[0:1]
	s_branch .LBB0_1435

; DEVI void attn_item(const P& p, int item, char* smem) {
;     ...
;     for (int mh = 0; mh < 2; ++mh) {
;         const int mo = mh * 32;
;         bf16x8 Qf[2][2];
; #pragma unroll
;         for (int m = 0; m < 2; ++m)
; #pragma unroll
;             for (int kk = 0; kk < 2; ++kk) Qf[m][kk] = *(const bf16x8*)(Q + (size_t)(mo + 16 * m + fr) * 1024 + kk * 32 + fq * 8);
;         f32x4 O[4][2];
; #pragma unroll
;         for (int nd = 0; nd < 4; ++nd)
; #pragma unroll
;             for (int m = 0; m < 2; ++m) O[nd][m] = (f32x4){0.f, 0.f, 0.f, 0.f};
;         float mrow[2], lrow[2];
; #pragma unroll
;         for (int m = 0; m < 2; ++m) { mrow[m] = sinkv; lrow[m] = (fq == 0) ? 1.0f : 0.0f; }
;         for (int ti = 0; ti < 9; ++ti) {
;             int tok0; bool lat;
;             if (ti < 5) { const int kb = q0 - 128 + 64 * ti; if (kb < 0 || kb >= SEQ) continue; tok0 = CTX + kb; lat = true; }
;             else { tok0 = (ti - 5) * 64; lat = false; }
.Lat_xpass:
	s_cmp_lg_u64 s[0:1], 0
	s_cbranch_scc1 .Lat_nopf
	s_add_i32 s100, s43, 0xffffff00
	s_cmpk_lt_u32 s100, 0x1000
	s_cbranch_scc0 .Lat_xp1
	s_mov_b32 s100, s43
	s_branch .Lat_xq
.Lat_xp1:
	s_sub_i32 s100, 0x100, s43
	s_cmp_lt_i32 s100, 1
	s_cbranch_scc1 .Lat_nopf
	s_add_i32 s100, s100, 63
	s_lshr_b32 s100, s100, 6
	s_cmp_gt_u32 s100, 4
	s_cbranch_scc1 .Lat_xctx
	s_lshl_b32 s100, s100, 6
	s_add_i32 s100, s100, s43
	s_branch .Lat_xq
.Lat_xctx:
	s_mov_b32 s100, 0
.Lat_xq:
	v_or_b32_e32 v248, 32, v174
	v_lshlrev_b32_e32 v250, 11, v248
	v_mov_b32_e32 v251, 0
	v_lshlrev_b32_e32 v248, 10, v248
	v_lshl_add_u64 v[250:251], v[108:109], 0, v[250:251]
	v_or_b32_e32 v248, 0x4000, v248
	v_lshlrev_b32_e32 v248, 1, v248
	v_mov_b32_e32 v249, 0
	global_load_dwordx4 v[232:235], v[250:251], off
	global_load_dwordx4 v[236:239], v[250:251], off offset:64
	v_lshl_add_u64 v[248:249], v[108:109], 0, v[248:249]
	global_load_dwordx4 v[240:243], v[248:249], off
	global_load_dwordx4 v[244:247], v[248:249], off offset:64
	s_branch .Lat_issue
